# P2x load balance: the 64 one-item workgroups run 6 RWKV sample iterations instead of 8, workgroups 0-127 run one each
# speedup vs baseline: 1.0906x; 1.0085x over previous
.LBB0_614:
	s_and_b32 s0, 0xffff, s33
	s_cmp_lg_u32 s0, 0
	s_cselect_b64 s[0:1], -1, 0
	s_cmp_lg_u64 s[0:1], 0
	v_readlane_b32 s0, v250, 0
	v_readlane_b32 s1, v250, 1
	s_load_dword s0, s[0:1], 0x0
	v_writelane_b32 v248, s78, 5
	v_mov_b32_e32 v183, v47
	s_waitcnt lgkmcnt(0)
	s_addc_u32 s0, s0, 0
	s_cmpk_lg_i32 s0, 0x100
	s_cselect_b64 s[0:1], -1, 0
	s_sub_u32 s2, s74, 0x80
	s_cmpk_lt_u32 s2, 0x40
	s_cselect_b64 s[2:3], -1, 0
	s_or_b64 s[0:1], s[2:3], s[0:1]
	s_cmpk_gt_i32 s74, 0x2bf
	s_cselect_b64 s[2:3], -1, 0
	s_lshr_b32 s33, s79, 8
	v_writelane_b32 v248, s33, 6
	s_mulk_i32 s33, 0x6800
	s_add_i32 s33, s33, 0
	s_lshl_b32 s38, s44, 2
	s_cmp_eq_u32 s44, 0
	s_cselect_b64 s[84:85], -1, 0
	s_cmp_lg_u32 s44, 0
	s_cselect_b64 s[40:41], -1, 0
	s_cmp_eq_u32 s44, 1
	v_writelane_b32 v249, s40, 60
	s_cselect_b64 s[72:73], -1, 0
	s_cmp_lt_u32 s44, 2
	v_writelane_b32 v249, s41, 61
	s_cselect_b64 s[40:41], -1, 0
	v_writelane_b32 v248, s40, 7
	s_or_b32 s42, s38, 1
	v_writelane_b32 v249, s38, 58
	v_writelane_b32 v248, s41, 8
	s_lshl_b32 s38, s44, 10
	s_lshl_b32 s39, s42, 8
	v_writelane_b32 v248, s39, 9
	s_or_b32 s39, s38, 0x200
	v_writelane_b32 v248, s39, 10
	v_writelane_b32 v249, s38, 62
	s_or_b32 s38, s38, 0x300
	v_writelane_b32 v248, s38, 11
	s_lshl_b32 s38, s44, 8
	s_add_i32 s38, s33, s38
	s_cmp_eq_u32 s44, 3
	v_add_u32_e32 v67, s38, v50
	s_cselect_b64 s[38:39], -1, 0
	s_add_i32 s45, s45, s33
	v_mov_b32_e32 v0, s33
	s_movk_i32 s40, 0x90
	s_cmp_gt_u32 s44, 1
	s_mulk_i32 s44, 0x120
	v_mad_u32_u24 v2, v179, s40, v0
	v_add_u32_e32 v0, s44, v158
	s_mulk_i32 s42, 0x48
	s_cselect_b64 s[40:41], -1, 0
	v_lshl_add_u32 v71, v0, 1, s33
	v_add_u32_e32 v0, s42, v158
	s_add_i32 s43, s42, 0x48
	v_add3_u32 v69, s45, v166, v44
	v_lshl_add_u32 v73, v0, 1, s33
	v_add_u32_e32 v0, s43, v158
	s_addk_i32 s42, 0x90
	v_readlane_b32 s44, v250, 7
	v_lshl_add_u32 v75, v0, 1, s33
	v_add_u32_e32 v0, s42, v158
	v_cmp_gt_u32_e64 s[42:43], 32, v158
	v_readlane_b32 s52, v250, 15
	v_readlane_b32 s53, v250, 16
	v_readlane_b32 s54, v250, 17
	v_readlane_b32 s55, v250, 18
	v_readlane_b32 s56, v250, 19
	v_readlane_b32 s57, v250, 20
	v_readlane_b32 s58, v250, 21
	v_readlane_b32 s59, v250, 22
	v_writelane_b32 v248, s42, 12
	v_readlane_b32 s52, v250, 60
	v_readlane_b32 s66, v249, 10
	v_writelane_b32 v248, s43, 13
	v_readlane_b32 s45, v250, 8
	v_readlane_b32 s67, v249, 11
	s_add_u32 s44, s66, 0x2200000
	v_readlane_b32 s42, v248, 4
	s_addc_u32 s45, s67, 0
	s_lshl_b32 s42, s42, 1
	s_add_u32 s42, s44, s42
	v_lshl_add_u32 v77, v0, 1, s33
	v_lshlrev_b32_e32 v0, 1, v45
	v_readlane_b32 s60, v249, 4
	v_readlane_b32 s61, v249, 5
	v_writelane_b32 v248, s44, 14
	s_addc_u32 s43, s45, 0
	v_mov_b32_e32 v45, v47
	v_add3_u32 v79, s33, v0, v44
	v_readlane_b32 s50, v250, 13
	v_readlane_b32 s51, v250, 14
	v_lshl_add_u64 v[60:61], s[42:43], 0, v[44:45]
	v_lshl_add_u64 v[0:1], s[66:67], 0, v[182:183]
	s_mov_b64 s[42:43], 0x4746000
	s_or_b64 s[0:1], s[2:3], s[0:1]
	v_readlane_b32 s60, v249, 16
	v_add_u32_e32 v65, s33, v50
	v_lshl_add_u32 v81, v179, 2, s33
	v_lshl_add_u64 v[58:59], s[50:51], 0, v[182:183]
	v_lshl_add_u64 v[62:63], v[0:1], 0, s[42:43]
	s_and_b64 vcc, exec, s[0:1]
	v_add_u32_e32 v83, v2, v159
	v_cndmask_b32_e64 v85, 0, 1, s[72:73]
	v_readlane_b32 s61, v249, 17
	v_readlane_b32 s46, v250, 9
	v_readlane_b32 s47, v250, 10
	v_readlane_b32 s48, v250, 11
	v_readlane_b32 s49, v250, 12
	v_readlane_b32 s53, v250, 61
	v_readlane_b32 s54, v250, 62
	v_readlane_b32 s55, v250, 63
	v_readlane_b32 s56, v249, 0
	v_readlane_b32 s57, v249, 1
	v_readlane_b32 s58, v249, 2
	v_readlane_b32 s59, v249, 3
	v_readlane_b32 s62, v249, 6
	v_readlane_b32 s63, v249, 7
	v_readlane_b32 s64, v249, 8
	v_readlane_b32 s65, v249, 9
	v_writelane_b32 v248, s45, 15
	s_cbranch_vccnz .LBB0_648
	v_readlane_b32 s0, v249, 45
	s_mov_b32 s0, s74
	s_cmpk_lt_u32 s0, 0x80
	s_cselect_b32 s1, 0x240, 0
	s_add_i32 s0, s0, s1
	s_add_i32 s42, s0, 0xffffff00
	s_lshl_b32 s0, s0, 1
	v_readlane_b32 s1, v248, 6
	s_add_i32 s0, s1, s0
	s_add_i32 s43, s0, 0xfffffe80
	v_mov_b32_e32 v21, 0
	s_lshl_b32 s74, s43, 6
	s_mov_b32 s79, 0
	s_mov_b32 s80, 0xf800000
	v_mov_b32_e32 v40, 0x260
	s_movk_i32 s81, 0x7fff
	v_mov_b32_e32 v41, 0xe00
	s_branch .LBB0_617
.LBB0_616:
	s_or_b64 exec, exec, s[0:1]
	v_add_u32_e32 v20, s33, v182
	v_lshlrev_b64 v[16:17], 6, v[22:23]
	ds_read_b128 v[28:31], v20 offset:13568
	ds_read_u16 v22, v79 offset:4752
	v_add_u32_e32 v32, 0x3400, v81
	ds_read2_b32 v[18:19], v32 offset0:64 offset1:80
	s_add_i32 s42, s42, 64
	s_waitcnt lgkmcnt(2)
	v_pk_mul_f32 v[12:13], v[12:13], v[28:29]
	s_waitcnt lgkmcnt(1)
	v_lshlrev_b32_e32 v23, 16, v22
	ds_read_u16 v22, v79 offset:4608
	ds_read_u16 v33, v79 offset:4640
	v_pk_mul_f32 v[14:15], v[14:15], v[30:31]
	s_addk_i32 s43, 0x80
	s_addk_i32 s74, 0x2000
	s_waitcnt lgkmcnt(1)
	v_lshlrev_b32_e32 v22, 16, v22
	v_pk_mul_f32 v[22:23], v[18:19], v[22:23] op_sel_hi:[0,1]
	v_cvt_pk_bf16_f32 v22, v22, v23
	ds_read_u16 v23, v79 offset:4896
	ds_read_u16 v28, v79 offset:5040
	v_lshl_add_u64 v[16:17], v[16:17], 2, v[62:63]
	s_cmpk_lt_i32 s42, 0x140
	s_waitcnt lgkmcnt(0)
	v_lshlrev_b32_e32 v29, 16, v28
	v_lshlrev_b32_e32 v28, 16, v23
	v_pk_mul_f32 v[28:29], v[18:19], v[28:29] op_sel_hi:[0,1]
	v_cvt_pk_bf16_f32 v23, v28, v29
	s_nop 1
	v_mfma_f32_16x16x16_bf16 v[12:15], v[22:23], v[26:27], v[12:15]
	ds_read_u16 v22, v79 offset:6912
	ds_read_u16 v23, v79 offset:7056
	s_waitcnt lgkmcnt(1)
	v_lshlrev_b32_e32 v22, 16, v22
	s_waitcnt lgkmcnt(0)
	v_lshlrev_b32_e32 v23, 16, v23
	v_pk_mul_f32 v[22:23], v[18:19], v[22:23] op_sel_hi:[0,1]
	v_cvt_pk_bf16_f32 v22, v22, v23
	ds_read_u16 v23, v79 offset:7200
	ds_read_u16 v28, v79 offset:7344
	s_waitcnt lgkmcnt(0)
	v_lshlrev_b32_e32 v29, 16, v28
	v_lshlrev_b32_e32 v28, 16, v23
	v_pk_mul_f32 v[28:29], v[18:19], v[28:29] op_sel_hi:[0,1]
	v_cvt_pk_bf16_f32 v23, v28, v29
	ds_read_b128 v[28:31], v20 offset:13632
	ds_read_u16 v18, v79 offset:4784
	v_mfma_f32_16x16x16_bf16 v[12:15], v[22:23], v[24:25], v[12:15]
	v_lshlrev_b32_e32 v22, 16, v33
	s_waitcnt lgkmcnt(0)
	v_lshlrev_b32_e32 v23, 16, v18
	v_mov_b32_e32 v18, v19
	v_pk_mul_f32 v[22:23], v[18:19], v[22:23] op_sel_hi:[0,1]
	v_cvt_pk_bf16_f32 v22, v22, v23
	ds_read_u16 v19, v79 offset:4928
	ds_read_u16 v23, v79 offset:5072
	v_pk_mul_f32 v[8:9], v[8:9], v[28:29]
	v_pk_mul_f32 v[10:11], v[10:11], v[30:31]
	s_waitcnt lgkmcnt(1)
	v_lshlrev_b32_e32 v28, 16, v19
	s_waitcnt lgkmcnt(0)
	v_lshlrev_b32_e32 v29, 16, v23
	v_pk_mul_f32 v[28:29], v[18:19], v[28:29] op_sel_hi:[0,1]
	v_cvt_pk_bf16_f32 v23, v28, v29
	s_nop 1
	v_mfma_f32_16x16x16_bf16 v[8:11], v[22:23], v[26:27], v[8:11]
	ds_read_u16 v19, v79 offset:6944
	ds_read_u16 v22, v79 offset:7088
	s_waitcnt lgkmcnt(0)
	v_lshlrev_b32_e32 v23, 16, v22
	v_lshlrev_b32_e32 v22, 16, v19
	v_pk_mul_f32 v[22:23], v[18:19], v[22:23] op_sel_hi:[0,1]
	v_cvt_pk_bf16_f32 v22, v22, v23
	ds_read_u16 v19, v79 offset:7232
	ds_read_u16 v23, v79 offset:7376
	s_waitcnt lgkmcnt(1)
	v_lshlrev_b32_e32 v28, 16, v19
	s_waitcnt lgkmcnt(0)
	v_lshlrev_b32_e32 v29, 16, v23
	v_pk_mul_f32 v[18:19], v[18:19], v[28:29] op_sel_hi:[0,1]
	v_cvt_pk_bf16_f32 v23, v18, v19
	ds_read_b128 v[28:31], v20 offset:13696
	ds_read2_b32 v[18:19], v32 offset0:96 offset1:112
	v_mfma_f32_16x16x16_bf16 v[8:11], v[22:23], v[24:25], v[8:11]
	ds_read_u16 v22, v79 offset:4672
	ds_read_u16 v23, v79 offset:4816
	s_waitcnt lgkmcnt(3)
	v_pk_mul_f32 v[4:5], v[4:5], v[28:29]
	v_pk_mul_f32 v[6:7], v[6:7], v[30:31]
	s_waitcnt lgkmcnt(1)
	v_lshlrev_b32_e32 v22, 16, v22
	s_waitcnt lgkmcnt(0)
	v_lshlrev_b32_e32 v23, 16, v23
	v_pk_mul_f32 v[22:23], v[18:19], v[22:23] op_sel_hi:[0,1]
	v_cvt_pk_bf16_f32 v22, v22, v23
	ds_read_u16 v23, v79 offset:4960
	ds_read_u16 v28, v79 offset:5104
	s_waitcnt lgkmcnt(0)
	v_lshlrev_b32_e32 v29, 16, v28
	v_lshlrev_b32_e32 v28, 16, v23
	v_pk_mul_f32 v[28:29], v[18:19], v[28:29] op_sel_hi:[0,1]
	v_cvt_pk_bf16_f32 v23, v28, v29
	s_nop 1
	v_mfma_f32_16x16x16_bf16 v[4:7], v[22:23], v[26:27], v[4:7]
	ds_read_u16 v22, v79 offset:6976
	ds_read_u16 v23, v79 offset:7120
	s_waitcnt lgkmcnt(1)
	v_lshlrev_b32_e32 v22, 16, v22
	s_waitcnt lgkmcnt(0)
	v_lshlrev_b32_e32 v23, 16, v23
	v_pk_mul_f32 v[22:23], v[18:19], v[22:23] op_sel_hi:[0,1]
	v_cvt_pk_bf16_f32 v22, v22, v23
	ds_read_u16 v23, v79 offset:7264
	ds_read_u16 v28, v79 offset:7408
	s_waitcnt lgkmcnt(0)
	v_lshlrev_b32_e32 v29, 16, v28
	v_lshlrev_b32_e32 v28, 16, v23
	v_pk_mul_f32 v[28:29], v[18:19], v[28:29] op_sel_hi:[0,1]
	v_cvt_pk_bf16_f32 v23, v28, v29
	ds_read_b128 v[28:31], v20 offset:13760
	s_waitcnt lgkmcnt(0)
	v_pk_mul_f32 v[28:29], v[0:1], v[28:29]
	ds_read_u16 v0, v79 offset:4704
	ds_read_u16 v1, v79 offset:4848
	v_pk_mul_f32 v[30:31], v[2:3], v[30:31]
	v_mfma_f32_16x16x16_bf16 v[4:7], v[22:23], v[24:25], v[4:7]
	s_waitcnt lgkmcnt(1)
	v_lshlrev_b32_e32 v2, 16, v0
	s_waitcnt lgkmcnt(0)
	v_lshlrev_b32_e32 v3, 16, v1
	v_mov_b32_e32 v0, v19
	v_pk_mul_f32 v[2:3], v[0:1], v[2:3] op_sel_hi:[0,1]
	v_cvt_pk_bf16_f32 v2, v2, v3
	ds_read_u16 v1, v79 offset:4992
	ds_read_u16 v3, v79 offset:5136
	s_waitcnt lgkmcnt(1)
	v_lshlrev_b32_e32 v18, 16, v1
	s_waitcnt lgkmcnt(0)
	v_lshlrev_b32_e32 v19, 16, v3
	v_pk_mul_f32 v[18:19], v[0:1], v[18:19] op_sel_hi:[0,1]
	v_cvt_pk_bf16_f32 v3, v18, v19
	s_nop 1
	v_mfma_f32_16x16x16_bf16 v[26:29], v[2:3], v[26:27], v[28:31]
	ds_read_u16 v1, v79 offset:7008
	ds_read_u16 v2, v79 offset:7152
	s_waitcnt lgkmcnt(0)
	v_lshlrev_b32_e32 v3, 16, v2
	v_lshlrev_b32_e32 v2, 16, v1
	v_pk_mul_f32 v[2:3], v[0:1], v[2:3] op_sel_hi:[0,1]
	v_cvt_pk_bf16_f32 v2, v2, v3
	ds_read_u16 v1, v79 offset:7296
	ds_read_u16 v3, v79 offset:7440
	s_waitcnt lgkmcnt(1)
	v_lshlrev_b32_e32 v18, 16, v1
	s_waitcnt lgkmcnt(0)
	v_lshlrev_b32_e32 v19, 16, v3
	v_pk_mul_f32 v[0:1], v[0:1], v[18:19] op_sel_hi:[0,1]
	v_cvt_pk_bf16_f32 v3, v0, v1
	s_nop 1
	v_mfma_f32_16x16x16_bf16 v[0:3], v[2:3], v[24:25], v[26:29]
	global_store_dwordx4 v[16:17], v[12:15], off
	global_store_dwordx4 v[16:17], v[8:11], off offset:64
	global_store_dwordx4 v[16:17], v[4:7], off offset:128
	s_nop 4
	global_store_dwordx4 v[16:17], v[0:3], off offset:192
	s_cbranch_scc0 .LBB0_648
